# v31 + grid-barrier spin loops poll with s_sleep 4 instead of s_sleep 1 (less polling traffic against the leaders' atomics)
# speedup vs baseline: 1.0102x; 1.0042x over previous
.LBB0_1308:
	s_and_b32 s18, s40, 0xff
	s_mov_b64 s[16:17], -1
	s_cmp_lg_u32 s18, 0
	s_mov_b64 s[38:39], -1
	s_sleep 4
	s_cbranch_scc1 .LBB0_1311
	v_readlane_b32 s18, v251, 45
	v_readlane_b32 s19, v251, 46
	s_nop 4
	global_load_dword v2, v1, s[18:19] sc1
	s_waitcnt vmcnt(0)
	v_cmp_eq_u32_e32 vcc, 0, v2
	s_cbranch_vccnz .LBB0_1313
	s_mov_b64 s[38:39], 0
	s_mov_b64 s[18:19], -1
